# NSA compressed-branch pass 2: the 32 bias-table LDS lookups per tile issued up front (were a two-deep read-wait-fma chain)
# baseline (speedup 1.0000x reference)
; #define LAS __attribute__((address_space(3)))
; __device__ __forceinline__ float ex2(float x) { return __builtin_amdgcn_exp2f(x); }
; __device__ __forceinline__ int crow(int r, int hi) { return (r & 3) + 8 * (r >> 2) + 4 * hi; }
; __device__ __forceinline__ v16f mfma32(v8s a, v8s b, v16f c) { return __builtin_amdgcn_mfma_f32_32x32x16_bf16(a, b, c, 0, 0, 0); }
; __device__ __forceinline__ void qk_tile(const LAS unsigned char* Kt, const v8s (&qf)[4], v16f& p0, v16f& p1, int r32, int hi) {
;     ...
;     for (int s = 0; s < 4; ++s) {
;         const v8s a0 = *(const LAS v8s*)(kb + s * 32);
;         const v8s a1 = *(const LAS v8s*)(kb + 32 * KP + s * 32);
;         p0 = mfma32(a0, qf[s], p0); p1 = mfma32(a1, qf[s], p1);
;     }
; __device__ __forceinline__ void nsa_phase(LAS unsigned char* lds, const bf16_t* QKV, const float* relb, const bf16_t* KCMP, const bf16_t* VCMP, bf16_t* AO, float* SCRG, unsigned* CTR, const float* sinks) {
;     ...
;                 qk_tile(KT + buf * KTB, qf, p0, p1, r32, hi);
; #pragma unroll
;                 for (int r = 0; r < 16; ++r) {
;                     const int c0 = 64 * t + crow(r, hi); const int d0 = qpos - 16 * c0 - 31, d1 = d0 - 512;
;                     p0[r] = ex2(p0[r] * C1 + tb[min(max(d0, -1), 1024)] - mu) * il; p1[r] = ex2(p1[r] * C1 + tb[min(max(d1, -1), 1024)] - mu) * il;
.LBB0_501:
	v_add3_u32 v118, s4, v103, v104
	ds_read_b128 v[34:37], v118 offset:4608
	ds_read_b128 v[38:41], v118
	ds_read_b128 v[110:113], v118 offset:32
	ds_read_b128 v[114:117], v118 offset:4640
	v_cmp_gt_u32_e32 vcc, 55, v98
	s_waitcnt lgkmcnt(2)
	v_mfma_f32_32x32x16_bf16 v[50:65], v[38:41], v[130:133], 0
	v_mfma_f32_32x32x16_bf16 v[34:49], v[34:37], v[130:133], 0
	s_waitcnt lgkmcnt(1)
	v_mfma_f32_32x32x16_bf16 v[50:65], v[110:113], v[134:137], v[50:65]
	s_waitcnt lgkmcnt(0)
	v_mfma_f32_32x32x16_bf16 v[34:49], v[114:117], v[134:137], v[34:49]
	ds_read_b128 v[110:113], v118 offset:64
	ds_read_b128 v[114:117], v118 offset:4672
	s_waitcnt lgkmcnt(1)
	v_mfma_f32_32x32x16_bf16 v[50:65], v[110:113], v[138:141], v[50:65]
	s_waitcnt lgkmcnt(0)
	v_mfma_f32_32x32x16_bf16 v[34:49], v[114:117], v[138:141], v[34:49]
	ds_read_b128 v[110:113], v118 offset:96
	ds_read_b128 v[114:117], v118 offset:4704
	s_waitcnt lgkmcnt(1)
	v_mfma_f32_32x32x16_bf16 v[50:65], v[110:113], v[142:145], v[50:65]
	v_add_u32_e32 v187, 0x1b0, v108
	v_med3_i32 v187, v187, 30, v242
	v_lshl_add_u32 v187, v187, 2, s37
	ds_read_b32 v155, v187 offset:53636
	v_add_u32_e32 v188, 32, v108
	v_med3_i32 v188, v188, 30, v242
	v_lshl_add_u32 v188, v188, 2, s37
	ds_read_b32 v156, v188 offset:53636
	v_add_u32_e32 v189, 0x1b0, v108
	v_med3_i32 v189, v189, s33, v243
	v_lshl_add_u32 v189, v189, 2, s37
	ds_read_b32 v157, v189 offset:51588
	v_add_u32_e32 v190, 0x1a0, v108
	v_med3_i32 v190, v190, 30, v242
	v_lshl_add_u32 v190, v190, 2, s37
	ds_read_b32 v158, v190 offset:53636
	v_add_u32_e32 v187, 0x1a0, v108
	v_med3_i32 v187, v187, s33, v243
	v_lshl_add_u32 v187, v187, 2, s37
	ds_read_b32 v159, v187 offset:51588
	v_add_u32_e32 v188, 32, v108
	v_med3_i32 v188, v188, s33, v243
	v_lshl_add_u32 v188, v188, 2, s37
	ds_read_b32 v160, v188 offset:51588
	v_add_u32_e32 v189, 0x190, v108
	v_med3_i32 v189, v189, 30, v242
	v_lshl_add_u32 v189, v189, 2, s37
	ds_read_b32 v161, v189 offset:53636
	v_add_u32_e32 v190, 0x190, v108
	v_med3_i32 v190, v190, s33, v243
	v_lshl_add_u32 v190, v190, 2, s37
	ds_read_b32 v162, v190 offset:51588
	v_add_u32_e32 v187, 0x180, v108
	v_med3_i32 v187, v187, 30, v242
	v_lshl_add_u32 v187, v187, 2, s37
	ds_read_b32 v163, v187 offset:53636
	v_add_u32_e32 v188, 0x180, v108
	v_med3_i32 v188, v188, s33, v243
	v_lshl_add_u32 v188, v188, 2, s37
	ds_read_b32 v164, v188 offset:51588
	v_add_u32_e32 v189, 0x130, v108
	v_med3_i32 v189, v189, 30, v242
	v_lshl_add_u32 v189, v189, 2, s37
	ds_read_b32 v165, v189 offset:53636
	v_add_u32_e32 v190, 0x130, v108
	v_med3_i32 v190, v190, s33, v243
	v_lshl_add_u32 v190, v190, 2, s37
	ds_read_b32 v166, v190 offset:51588
	v_add_u32_e32 v187, 0x120, v108
	v_med3_i32 v187, v187, 30, v242
	v_lshl_add_u32 v187, v187, 2, s37
	ds_read_b32 v167, v187 offset:53636
	v_add_u32_e32 v188, 0x120, v108
	v_med3_i32 v188, v188, s33, v243
	v_lshl_add_u32 v188, v188, 2, s37
	ds_read_b32 v168, v188 offset:51588
	v_add_u32_e32 v189, 0x110, v108
	v_med3_i32 v189, v189, 30, v242
	v_lshl_add_u32 v189, v189, 2, s37
	ds_read_b32 v169, v189 offset:53636
	v_add_u32_e32 v190, 0x110, v108
	v_med3_i32 v190, v190, s33, v243
	v_lshl_add_u32 v190, v190, 2, s37
	ds_read_b32 v170, v190 offset:51588
	v_add_u32_e32 v187, 0x100, v108
	v_med3_i32 v187, v187, 30, v242
	v_lshl_add_u32 v187, v187, 2, s37
	ds_read_b32 v171, v187 offset:53636
	v_add_u32_e32 v188, 0x100, v108
	v_med3_i32 v188, v188, s33, v243
	v_lshl_add_u32 v188, v188, 2, s37
	ds_read_b32 v172, v188 offset:51588
	v_add_u32_e32 v189, 0xb0, v108
	v_med3_i32 v189, v189, 30, v242
	v_lshl_add_u32 v189, v189, 2, s37
	ds_read_b32 v173, v189 offset:53636
	v_add_u32_e32 v190, 0xb0, v108
	v_med3_i32 v190, v190, s33, v243
	v_lshl_add_u32 v190, v190, 2, s37
	ds_read_b32 v174, v190 offset:51588
	v_add_u32_e32 v187, 0xa0, v108
	v_med3_i32 v187, v187, 30, v242
	v_lshl_add_u32 v187, v187, 2, s37
	ds_read_b32 v175, v187 offset:53636
	v_add_u32_e32 v188, 0xa0, v108
	v_med3_i32 v188, v188, s33, v243
	v_lshl_add_u32 v188, v188, 2, s37
	ds_read_b32 v176, v188 offset:51588
	v_add_u32_e32 v189, 0x90, v108
	v_med3_i32 v189, v189, 30, v242
	v_lshl_add_u32 v189, v189, 2, s37
	ds_read_b32 v177, v189 offset:53636
	v_add_u32_e32 v190, 0x90, v108
	v_med3_i32 v190, v190, s33, v243
	v_lshl_add_u32 v190, v190, 2, s37
	ds_read_b32 v178, v190 offset:51588
	v_add_u32_e32 v187, 0x80, v108
	v_med3_i32 v187, v187, 30, v242
	v_lshl_add_u32 v187, v187, 2, s37
	ds_read_b32 v179, v187 offset:53636
	v_add_u32_e32 v188, 0x80, v108
	v_med3_i32 v188, v188, s33, v243
	v_lshl_add_u32 v188, v188, 2, s37
	ds_read_b32 v180, v188 offset:51588
	v_add_u32_e32 v189, 48, v108
	v_med3_i32 v189, v189, 30, v242
	v_lshl_add_u32 v189, v189, 2, s37
	ds_read_b32 v181, v189 offset:53636
	v_add_u32_e32 v190, 48, v108
	v_med3_i32 v190, v190, s33, v243
	v_lshl_add_u32 v190, v190, 2, s37
	ds_read_b32 v182, v190 offset:51588
	v_add_u32_e32 v187, 16, v108
	v_med3_i32 v187, v187, 30, v242
	v_lshl_add_u32 v187, v187, 2, s37
	ds_read_b32 v183, v187 offset:53636
	v_add_u32_e32 v188, 16, v108
	v_med3_i32 v188, v188, s33, v243
	v_lshl_add_u32 v188, v188, 2, s37
	ds_read_b32 v184, v188 offset:51588
	v_add_u32_e32 v189, 0, v108
	v_med3_i32 v189, v189, 30, v242
	v_lshl_add_u32 v189, v189, 2, s37
	ds_read_b32 v185, v189 offset:53636
	v_add_u32_e32 v190, 0, v108
	v_med3_i32 v190, v190, s33, v243
	v_lshl_add_u32 v190, v190, 2, s37
	ds_read_b32 v186, v190 offset:51588
	v_add_u32_e32 v110, 0x1b0, v108
	v_add_u32_e32 v112, 32, v108
	v_med3_i32 v111, v110, 30, v242
	v_med3_i32 v110, v110, s33, v243
	v_med3_i32 v113, v112, 30, v242
	v_lshl_add_u32 v111, v111, 2, s37
	v_lshl_add_u32 v110, v110, 2, s37
	s_waitcnt lgkmcnt(0)
; __device__ __forceinline__ float ex2(float x) { return __builtin_amdgcn_exp2f(x); }
; __device__ __forceinline__ void lds_add(LAS unsigned* p, unsigned v) { (void)__hip_atomic_fetch_add(p, v, __ATOMIC_RELAXED, __HIP_MEMORY_SCOPE_WORKGROUP); }
; __device__ __forceinline__ int crow(int r, int hi) { return (r & 3) + 8 * (r >> 2) + 4 * hi; }
; __device__ __forceinline__ void nsa_phase(LAS unsigned char* lds, const bf16_t* QKV, const float* relb, const bf16_t* KCMP, const bf16_t* VCMP, bf16_t* AO, float* SCRG, unsigned* CTR, const float* sinks) {
;     ...
;                 for (int r = 0; r < 16; ++r) {
;                     const int c0 = 64 * t + crow(r, hi); const int d0 = qpos - 16 * c0 - 31, d1 = d0 - 512;
;                     p0[r] = ex2(p0[r] * C1 + tb[min(max(d0, -1), 1024)] - mu) * il; p1[r] = ex2(p1[r] * C1 + tb[min(max(d1, -1), 1024)] - mu) * il;
;                 }
; #pragma unroll
;                 for (int gq = 0; gq < 4; ++gq) {
;                     const int sb0 = 16 * t + 2 * gq + hi, sb1 = sb0 + 8;
;                     const unsigned a0 = (unsigned)(((p0[4 * gq] + p0[4 * gq + 1]) + (p0[4 * gq + 2] + p0[4 * gq + 3])) * 4194304.f + 0.5f);
;                     const unsigned a1 = (unsigned)(((p1[4 * gq] + p1[4 * gq + 1]) + (p1[4 * gq + 2] + p1[4 * gq + 3])) * 4194304.f + 0.5f);
;                     const unsigned e0 = (unsigned)(p0[4 * gq + 3] * 4194304.f + 0.5f), e1 = (unsigned)(p1[4 * gq + 3] * 4194304.f + 0.5f);
;                     lds_add(IMP + r32 * 64 + sb0, a0); lds_add(IMP + r32 * 64 + sb1, a1);
;                     lds_add(IMP + r32 * 64 + sb0 + 1, e0); if (sb1 + 1 < 64) lds_add(IMP + r32 * 64 + sb1 + 1, e1);
;                 }
	v_mfma_f32_32x32x16_bf16 v[34:49], v[114:117], v[142:145], v[34:49]
	s_waitcnt lgkmcnt(0)
	s_nop 7
	s_nop 7
	v_lshl_add_u32 v113, v113, 2, s37
	v_med3_i32 v112, v112, s33, v243
	v_lshl_add_u32 v112, v112, 2, s37
	v_fma_f32 v111, v50, s52, v155
	v_sub_f32_e32 v50, v111, v75
	s_nop 1
	v_fma_f32 v110, v34, s52, v157
	v_sub_f32_e32 v34, v110, v75
	v_add_u32_e32 v110, 0x1a0, v108
	v_med3_i32 v111, v110, 30, v242
	v_med3_i32 v110, v110, s33, v243
	v_lshl_add_u32 v111, v111, 2, s37
	v_lshl_add_u32 v110, v110, 2, s37
	v_exp_f32_e32 v50, v50
	v_exp_f32_e32 v34, v34
	v_fma_f32 v111, v51, s52, v158
	v_fma_f32 v110, v35, s52, v159
	v_sub_f32_e32 v35, v110, v75
	v_add_u32_e32 v110, 0x190, v108
	v_sub_f32_e32 v51, v111, v75
	v_med3_i32 v111, v110, 30, v242
	v_med3_i32 v110, v110, s33, v243
	v_lshl_add_u32 v111, v111, 2, s37
	v_lshl_add_u32 v110, v110, 2, s37
	v_add_u32_e32 v112, 16, v108
	v_med3_i32 v114, v112, 30, v242
	v_med3_i32 v112, v112, s33, v243
	v_fma_f32 v111, v52, s52, v161
	v_fma_f32 v110, v36, s52, v162
	v_sub_f32_e32 v36, v110, v75
	v_add_u32_e32 v110, 0x180, v108
	v_sub_f32_e32 v52, v111, v75
	v_med3_i32 v111, v110, 30, v242
	v_med3_i32 v110, v110, s33, v243
	v_lshl_add_u32 v111, v111, 2, s37
	v_lshl_add_u32 v110, v110, 2, s37
	v_exp_f32_e32 v51, v51
	v_exp_f32_e32 v52, v52
	v_lshl_add_u32 v114, v114, 2, s37
	v_fma_f32 v111, v53, s52, v163
	v_fma_f32 v110, v37, s52, v164
	v_sub_f32_e32 v37, v110, v75
	v_add_u32_e32 v110, 0x130, v108
	v_sub_f32_e32 v53, v111, v75
	v_med3_i32 v111, v110, 30, v242
	v_med3_i32 v110, v110, s33, v243
	v_lshl_add_u32 v111, v111, 2, s37
	v_lshl_add_u32 v110, v110, 2, s37
	v_add_u32_e32 v110, 0x120, v108
	v_med3_i32 v111, v110, 30, v242
	v_med3_i32 v110, v110, s33, v243
	v_lshl_add_u32 v111, v111, 2, s37
	v_lshl_add_u32 v110, v110, 2, s37
	v_add_u32_e32 v110, 0x110, v108
	v_med3_i32 v111, v110, 30, v242
	v_med3_i32 v110, v110, s33, v243
	v_lshl_add_u32 v111, v111, 2, s37
	v_lshl_add_u32 v110, v110, 2, s37
	v_add_u32_e32 v110, 0x100, v108
	v_med3_i32 v111, v110, 30, v242
	v_med3_i32 v110, v110, s33, v243
	v_lshl_add_u32 v111, v111, 2, s37
	v_lshl_add_u32 v110, v110, 2, s37
	v_add_u32_e32 v110, 0xb0, v108
	v_med3_i32 v111, v110, 30, v242
	v_med3_i32 v110, v110, s33, v243
	v_lshl_add_u32 v111, v111, 2, s37
	v_lshl_add_u32 v110, v110, 2, s37
	v_add_u32_e32 v110, 0xa0, v108
	v_med3_i32 v111, v110, 30, v242
	v_med3_i32 v110, v110, s33, v243
	v_lshl_add_u32 v111, v111, 2, s37
	v_lshl_add_u32 v110, v110, 2, s37
	v_add_u32_e32 v110, 0x90, v108
	v_med3_i32 v111, v110, 30, v242
	v_med3_i32 v110, v110, s33, v243
	v_lshl_add_u32 v111, v111, 2, s37
	v_lshl_add_u32 v110, v110, 2, s37
	v_add_u32_e32 v110, 0x80, v108
	v_med3_i32 v111, v110, 30, v242
	v_med3_i32 v110, v110, s33, v243
	v_lshl_add_u32 v111, v111, 2, s37
	v_lshl_add_u32 v110, v110, 2, s37
	v_add_u32_e32 v111, 48, v108
	v_med3_i32 v110, v111, 30, v242
	v_med3_i32 v111, v111, s33, v243
	v_lshl_add_u32 v110, v110, 2, s37
	v_lshl_add_u32 v111, v111, 2, s37
	v_exp_f32_e32 v53, v53
	v_lshl_add_u32 v112, v112, 2, s37
	v_med3_i32 v112, v108, 30, v242
	v_lshl_add_u32 v112, v112, 2, s37
	v_exp_f32_e32 v35, v35
	v_exp_f32_e32 v36, v36
	v_exp_f32_e32 v37, v37
	v_med3_i32 v112, v108, s33, v243
	v_pk_mul_f32 v[50:51], v[80:81], v[50:51]
	v_pk_mul_f32 v[52:53], v[80:81], v[52:53]
	v_lshl_add_u32 v112, v112, 2, s37
	v_add_f32_e32 v112, v52, v53
	v_add_f32_e32 v151, v50, v51
	v_add_f32_e32 v112, v151, v112
	v_pk_mul_f32 v[34:35], v[80:81], v[34:35]
	v_pk_mul_f32 v[36:37], v[80:81], v[36:37]
	v_fma_f32 v112, v112, s53, 0.5
	v_cvt_u32_f32_e32 v151, v112
	v_add_f32_e32 v112, v36, v37
	v_add_f32_e32 v152, v34, v35
	v_add_f32_e32 v112, v152, v112
	v_fma_f32 v112, v112, s53, 0.5
	v_cvt_u32_f32_e32 v152, v112
	v_fma_f32 v112, v53, s53, 0.5
	v_cvt_u32_f32_e32 v153, v112
	v_add_u32_e32 v112, s21, v107
	v_add_u32_e32 v154, 0x1bd00, v112
	ds_add_u32 v154, v151
	v_add_u32_e32 v151, 0x1bd20, v112
	ds_add_u32 v151, v152
	v_add_u32_e32 v151, 0x1bd04, v112
	ds_add_u32 v151, v153
	s_and_saveexec_b64 s[4:5], vcc
	s_cbranch_execz .LBB0_503
	v_fma_f32 v151, v37, s53, 0.5
	v_cvt_u32_f32_e32 v151, v151
	v_add_u32_e32 v152, 0x1bd24, v112
	ds_add_u32 v152, v151
; __device__ __forceinline__ float ex2(float x) { return __builtin_amdgcn_exp2f(x); }
; __device__ __forceinline__ void lds_add(LAS unsigned* p, unsigned v) { (void)__hip_atomic_fetch_add(p, v, __ATOMIC_RELAXED, __HIP_MEMORY_SCOPE_WORKGROUP); }
; __device__ __forceinline__ void nsa_phase(LAS unsigned char* lds, const bf16_t* QKV, const float* relb, const bf16_t* KCMP, const bf16_t* VCMP, bf16_t* AO, float* SCRG, unsigned* CTR, const float* sinks) {
;     ...
;                     p0[r] = ex2(p0[r] * C1 + tb[min(max(d0, -1), 1024)] - mu) * il; p1[r] = ex2(p1[r] * C1 + tb[min(max(d1, -1), 1024)] - mu) * il;
;                 }
; #pragma unroll
;                 for (int gq = 0; gq < 4; ++gq) {
;                     const int sb0 = 16 * t + 2 * gq + hi, sb1 = sb0 + 8;
;                     const unsigned a0 = (unsigned)(((p0[4 * gq] + p0[4 * gq + 1]) + (p0[4 * gq + 2] + p0[4 * gq + 3])) * 4194304.f + 0.5f);
;                     const unsigned a1 = (unsigned)(((p1[4 * gq] + p1[4 * gq + 1]) + (p1[4 * gq + 2] + p1[4 * gq + 3])) * 4194304.f + 0.5f);
;                     const unsigned e0 = (unsigned)(p0[4 * gq + 3] * 4194304.f + 0.5f), e1 = (unsigned)(p1[4 * gq + 3] * 4194304.f + 0.5f);
;                     lds_add(IMP + r32 * 64 + sb0, a0); lds_add(IMP + r32 * 64 + sb1, a1);
;                     lds_add(IMP + r32 * 64 + sb0 + 1, e0); if (sb1 + 1 < 64) lds_add(IMP + r32 * 64 + sb1 + 1, e1);
.LBB0_503:
	s_or_b64 exec, exec, s[4:5]
	v_fma_f32 v125, v54, s52, v165
	v_fma_f32 v129, v55, s52, v167
	v_fma_f32 v128, v56, s52, v169
	v_fma_f32 v148, v57, s52, v171
	v_sub_f32_e32 v54, v125, v75
	v_fma_f32 v126, v38, s52, v166
	v_sub_f32_e32 v55, v129, v75
	v_fma_f32 v127, v39, s52, v168
	v_sub_f32_e32 v56, v128, v75
	v_fma_f32 v146, v40, s52, v170
	v_sub_f32_e32 v57, v148, v75
	v_fma_f32 v150, v41, s52, v172
	v_exp_f32_e32 v54, v54
	v_sub_f32_e32 v38, v126, v75
	v_exp_f32_e32 v55, v55
	v_sub_f32_e32 v39, v127, v75
	v_exp_f32_e32 v56, v56
	v_sub_f32_e32 v40, v146, v75
	v_exp_f32_e32 v57, v57
	v_sub_f32_e32 v41, v150, v75
	v_exp_f32_e32 v38, v38
	v_exp_f32_e32 v39, v39
	v_exp_f32_e32 v40, v40
	v_exp_f32_e32 v41, v41
	v_pk_mul_f32 v[54:55], v[80:81], v[54:55]
	v_pk_mul_f32 v[56:57], v[80:81], v[56:57]
	v_pk_mul_f32 v[38:39], v[80:81], v[38:39]
	v_pk_mul_f32 v[40:41], v[80:81], v[40:41]
	v_add_f32_e32 v125, v56, v57
	v_add_f32_e32 v126, v54, v55
	v_add_f32_e32 v125, v126, v125
	v_add_f32_e32 v126, v40, v41
	v_add_f32_e32 v127, v38, v39
	v_fma_f32 v125, v125, s53, 0.5
	v_add_f32_e32 v126, v127, v126
	v_cvt_u32_f32_e32 v125, v125
	v_fma_f32 v126, v126, s53, 0.5
	v_cvt_u32_f32_e32 v126, v126
	v_fma_f32 v127, v57, s53, 0.5
	v_cvt_u32_f32_e32 v127, v127
	v_add_u32_e32 v128, 0x1bd08, v112
	ds_add_u32 v128, v125
	v_add_u32_e32 v125, 0x1bd28, v112
	ds_add_u32 v125, v126
	v_add_u32_e32 v125, 0x1bd0c, v112
	ds_add_u32 v125, v127
	v_add_u32_e32 v125, 2, v98
	v_cmp_gt_u32_e32 vcc, 55, v125
	s_and_saveexec_b64 s[4:5], vcc
	s_cbranch_execz .LBB0_505
	v_fma_f32 v125, v41, s53, 0.5
	v_cvt_u32_f32_e32 v125, v125
	v_add_u32_e32 v126, 0x1bd2c, v112
	ds_add_u32 v126, v125
.LBB0_505:
	s_or_b64 exec, exec, s[4:5]
	v_fma_f32 v118, v58, s52, v173
	v_fma_f32 v122, v59, s52, v175
	v_fma_f32 v121, v60, s52, v177
	v_fma_f32 v124, v61, s52, v179
	v_sub_f32_e32 v58, v118, v75
	v_fma_f32 v119, v42, s52, v174
	v_sub_f32_e32 v59, v122, v75
	v_fma_f32 v120, v43, s52, v176
	v_sub_f32_e32 v60, v121, v75
	v_fma_f32 v123, v44, s52, v178
	v_sub_f32_e32 v61, v124, v75
	v_fma_f32 v149, v45, s52, v180
	v_exp_f32_e32 v58, v58
	v_sub_f32_e32 v42, v119, v75
	v_exp_f32_e32 v59, v59
	v_sub_f32_e32 v43, v120, v75
	v_exp_f32_e32 v60, v60
	v_sub_f32_e32 v44, v123, v75
	v_exp_f32_e32 v61, v61
	v_sub_f32_e32 v45, v149, v75
	v_exp_f32_e32 v42, v42
	v_exp_f32_e32 v43, v43
	v_exp_f32_e32 v44, v44
	v_exp_f32_e32 v45, v45
	v_pk_mul_f32 v[58:59], v[80:81], v[58:59]
	v_pk_mul_f32 v[60:61], v[80:81], v[60:61]
	v_pk_mul_f32 v[42:43], v[80:81], v[42:43]
	v_pk_mul_f32 v[44:45], v[80:81], v[44:45]
	v_add_f32_e32 v118, v60, v61
	v_add_f32_e32 v119, v58, v59
	v_add_f32_e32 v118, v119, v118
	v_add_f32_e32 v119, v44, v45
	v_add_f32_e32 v120, v42, v43
	v_fma_f32 v118, v118, s53, 0.5
	v_add_f32_e32 v119, v120, v119
	v_cvt_u32_f32_e32 v118, v118
	v_fma_f32 v119, v119, s53, 0.5
	v_cvt_u32_f32_e32 v119, v119
	v_fma_f32 v120, v61, s53, 0.5
	v_cvt_u32_f32_e32 v120, v120
	v_add_u32_e32 v121, 0x1bd10, v112
	ds_add_u32 v121, v118
	v_add_u32_e32 v118, 0x1bd30, v112
	ds_add_u32 v118, v119
	v_add_u32_e32 v118, 0x1bd14, v112
	ds_add_u32 v118, v120
	v_add_u32_e32 v118, 4, v98
	v_cmp_gt_u32_e32 vcc, 55, v118
	s_and_saveexec_b64 s[4:5], vcc
	s_cbranch_execz .LBB0_507
	v_fma_f32 v118, v45, s53, 0.5
	v_cvt_u32_f32_e32 v118, v118
	v_add_u32_e32 v119, 0x1bd34, v112
	ds_add_u32 v119, v118
.LBB0_507:
	s_or_b64 exec, exec, s[4:5]
	v_fma_f32 v110, v62, s52, v181
	v_fma_f32 v115, v63, s52, v156
	v_fma_f32 v114, v64, s52, v183
	v_fma_f32 v117, v65, s52, v185
	v_sub_f32_e32 v62, v110, v75
	v_fma_f32 v111, v46, s52, v182
	v_sub_f32_e32 v63, v115, v75
	v_fma_f32 v113, v47, s52, v160
	v_sub_f32_e32 v64, v114, v75
	v_fma_f32 v116, v48, s52, v184
	v_sub_f32_e32 v65, v117, v75
	v_fma_f32 v147, v49, s52, v186
	v_exp_f32_e32 v62, v62
	v_sub_f32_e32 v46, v111, v75
	v_exp_f32_e32 v63, v63
	v_sub_f32_e32 v47, v113, v75
	v_exp_f32_e32 v64, v64
	v_sub_f32_e32 v48, v116, v75
	v_exp_f32_e32 v65, v65
	v_sub_f32_e32 v49, v147, v75
	v_exp_f32_e32 v46, v46
	v_exp_f32_e32 v47, v47
	v_exp_f32_e32 v48, v48
	v_exp_f32_e32 v49, v49
	v_pk_mul_f32 v[62:63], v[80:81], v[62:63]
	v_pk_mul_f32 v[64:65], v[80:81], v[64:65]
	v_pk_mul_f32 v[46:47], v[80:81], v[46:47]
	v_pk_mul_f32 v[48:49], v[80:81], v[48:49]
	v_add_f32_e32 v110, v64, v65
	v_add_f32_e32 v111, v62, v63
	v_add_f32_e32 v110, v111, v110
	v_add_f32_e32 v111, v48, v49
	v_add_f32_e32 v113, v46, v47
	v_fma_f32 v110, v110, s53, 0.5
	v_add_f32_e32 v111, v113, v111
	v_cvt_u32_f32_e32 v110, v110
	v_fma_f32 v111, v111, s53, 0.5
	v_cvt_u32_f32_e32 v111, v111
	v_fma_f32 v113, v65, s53, 0.5
	v_cvt_u32_f32_e32 v113, v113
	v_add_u32_e32 v114, 0x1bd18, v112
	ds_add_u32 v114, v110
	v_add_u32_e32 v110, 0x1bd38, v112
	ds_add_u32 v110, v111
	v_add_u32_e32 v110, 0x1bd1c, v112
	ds_add_u32 v110, v113
	v_add_u32_e32 v110, 6, v98
	v_cmp_gt_u32_e32 vcc, 55, v110
	s_and_saveexec_b64 s[4:5], vcc
	s_cbranch_execz .LBB0_498
	v_fma_f32 v110, v49, s53, 0.5
	v_cvt_u32_f32_e32 v110, v110
	v_add_u32_e32 v111, 0x1bd3c, v112
	ds_add_u32 v111, v110
	s_branch .LBB0_498
